# same as previous best but the filter tail uses only registers the compiler already treats as dead (v150-v181) for its LDS reads
# baseline (speedup 1.0000x reference)
.LBB0_192:
	s_or_b64 exec, exec, s[10:11]
	v_lshlrev_b32_e32 v0, 3, v144
	v_sub_u32_e32 v1, 0x800, v0
	v_add_u32_e32 v2, 0xfffff800, v0
	v_cmp_gt_u32_e32 vcc, 0x100, v144
	v_lshlrev_b32_e32 v1, 5, v1
	v_lshlrev_b32_e32 v2, 5, v2
	v_add_u32_e32 v2, 16, v2
	v_mov_b32_e32 v4, 32
	s_movk_i32 s14, 0x100
	v_mov_b32_e32 v3, 0xffffffe0
	v_cmp_eq_u32_e64 s[10:11], s14, v144
	v_cmp_eq_u32_e64 s[12:13], 0, v144
	v_cndmask_b32_e32 v5, v2, v1, vcc
	v_cndmask_b32_e32 v4, v4, v3, vcc
	v_mov_b32_e32 v13, 0x10900
	v_lshlrev_b32_e32 v18, 4, v144
	v_add_u32_e32 v6, v5, v4
	v_add_u32_e32 v7, v6, v4
	v_add_u32_e32 v8, v7, v4
	v_add_u32_e32 v9, v8, v4
	v_add_u32_e32 v10, v9, v4
	v_add_u32_e32 v11, v10, v4
	v_add_u32_e32 v12, v11, v4
	v_cndmask_b32_e64 v5, v5, 0, s[10:11]
	ds_read_b128 v[14:17], v13
	ds_read_b128 v[150:153], v5
	ds_read_b128 v[154:157], v6
	ds_read_b128 v[158:161], v7
	ds_read_b128 v[162:165], v8
	ds_read_b128 v[166:169], v9
	ds_read_b128 v[170:173], v10
	ds_read_b128 v[174:177], v11
	ds_read_b128 v[178:181], v12
	s_waitcnt lgkmcnt(0)
	v_mul_f32_e32 v20, v150, v14
	v_mul_f32_e32 v21, v154, v14
	v_mul_f32_e32 v22, v158, v14
	v_mul_f32_e32 v23, v162, v14
	v_mul_f32_e32 v24, v166, v14
	v_mul_f32_e32 v25, v170, v14
	v_mul_f32_e32 v26, v174, v14
	v_mul_f32_e32 v27, v178, v14
	v_cndmask_b32_e64 v20, v20, 0, s[12:13]
	v_cvt_pk_bf16_f32 v0, v20, v21
	v_cvt_pk_bf16_f32 v1, v22, v23
	v_cvt_pk_bf16_f32 v2, v24, v25
	v_cvt_pk_bf16_f32 v3, v26, v27
	global_store_dwordx4 v18, v[0:3], s[72:73]
	v_mul_f32_e32 v20, v151, v15
	v_mul_f32_e32 v21, v155, v15
	v_mul_f32_e32 v22, v159, v15
	v_mul_f32_e32 v23, v163, v15
	v_mul_f32_e32 v24, v167, v15
	v_mul_f32_e32 v25, v171, v15
	v_mul_f32_e32 v26, v175, v15
	v_mul_f32_e32 v27, v179, v15
	v_cndmask_b32_e64 v20, v20, 0, s[12:13]
	v_cvt_pk_bf16_f32 v0, v20, v21
	v_cvt_pk_bf16_f32 v1, v22, v23
	v_cvt_pk_bf16_f32 v2, v24, v25
	v_cvt_pk_bf16_f32 v3, v26, v27
	s_add_u32 s14, s72, 0x2000
	s_addc_u32 s15, s73, 0
	global_store_dwordx4 v18, v[0:3], s[14:15]
	v_mul_f32_e32 v20, v152, v16
	v_mul_f32_e32 v21, v156, v16
	v_mul_f32_e32 v22, v160, v16
	v_mul_f32_e32 v23, v164, v16
	v_mul_f32_e32 v24, v168, v16
	v_mul_f32_e32 v25, v172, v16
	v_mul_f32_e32 v26, v176, v16
	v_mul_f32_e32 v27, v180, v16
	v_cndmask_b32_e64 v20, v20, 0, s[12:13]
	v_cvt_pk_bf16_f32 v0, v20, v21
	v_cvt_pk_bf16_f32 v1, v22, v23
	v_cvt_pk_bf16_f32 v2, v24, v25
	v_cvt_pk_bf16_f32 v3, v26, v27
	s_add_u32 s14, s72, 0x4000
	s_addc_u32 s15, s73, 0
	global_store_dwordx4 v18, v[0:3], s[14:15]
	v_mul_f32_e32 v20, v153, v17
	v_mul_f32_e32 v21, v157, v17
	v_mul_f32_e32 v22, v161, v17
	v_mul_f32_e32 v23, v165, v17
	v_mul_f32_e32 v24, v169, v17
	v_mul_f32_e32 v25, v173, v17
	v_mul_f32_e32 v26, v177, v17
	v_mul_f32_e32 v27, v181, v17
	v_cndmask_b32_e64 v20, v20, 0, s[12:13]
	v_cvt_pk_bf16_f32 v0, v20, v21
	v_cvt_pk_bf16_f32 v1, v22, v23
	v_cvt_pk_bf16_f32 v2, v24, v25
	v_cvt_pk_bf16_f32 v3, v26, v27
	s_add_u32 s14, s72, 0x6000
	s_addc_u32 s15, s73, 0
	global_store_dwordx4 v18, v[0:3], s[14:15]
	s_mov_b64 s[74:75], 0
	s_branch .LBB0_161
